# fused-LN units: residual loads issued before the wait for the K-loop's last staging loads (one combined wait + barrier)
# speedup vs baseline: 1.0070x; 1.0070x over previous
; __device__ __forceinline__ int lane_now() { int l; asm volatile("v_mbcnt_lo_u32_b32 %0, -1, 0\n\tv_mbcnt_hi_u32_b32 %0, -1, %0" : "=v"(l)); return l; }
; #define PG8_WAIT_V(n) asm volatile("s_waitcnt vmcnt(" #n ")" ::: "memory")
; #define PG8_BAR __builtin_amdgcn_s_barrier()
; template <bool F8 = false, class Sched, class Epi>
; __device__ __forceinline__ void gemm_phase(LAS unsigned char* lds, const Sched& S, const Epi& E) {
;     ...
;     PG8_WAIT_V(0);
;     PG8_BAR;
;     if (Epi::after_drain(cur.kind) && !E.skip) { const int le = lane_now(); E.fused(acc, cur, wr, wc, le & 15, le >> 4, lds, wid, le); }
.LBB0_427:
	s_cmp_eq_u32 s70, 7
	s_cbranch_scc1 .Ldrain_later
	s_cmp_eq_u32 s70, 11
	s_cbranch_scc1 .Ldrain_later
	s_waitcnt vmcnt(0)
.Ldrain_later:
	v_readlane_b32 s66, v254, 60
	v_readlane_b32 s18, v254, 40
	v_readlane_b32 s20, v254, 43
	v_readlane_b32 s80, v254, 46
	v_readlane_b32 s74, v254, 48
	v_readlane_b32 s68, v254, 50
	v_readlane_b32 s82, v254, 53
	v_readlane_b32 s84, v254, 55
	v_readlane_b32 s26, v255, 17
	v_readlane_b32 s16, v255, 15
	s_cmp_lt_i32 s70, 11
	v_readlane_b32 s67, v254, 61
	v_readlane_b32 s92, v254, 62
	s_mov_b32 s36, s18
	v_readlane_b32 s44, v254, 42
	v_readlane_b32 s21, v254, 44
	v_readlane_b32 s50, v254, 45
	s_mov_b32 s45, s54
	v_readlane_b32 s81, v254, 47
	v_readlane_b32 s75, v254, 49
	v_readlane_b32 s69, v254, 51
	v_readlane_b32 s83, v254, 54
	v_readlane_b32 s85, v254, 56
	v_readlane_b32 s86, v254, 58
	v_readlane_b32 s87, v254, 59
	s_movk_i32 s89, 0x800
	v_readlane_b32 s90, v255, 6
	s_mov_b32 s91, s63
	v_readlane_b32 s72, v255, 21
	v_readlane_b32 s27, v255, 18
	v_readlane_b32 s17, v255, 16
	s_barrier
	v_readlane_b32 s19, v254, 41
	s_cbranch_scc1 .LBB0_429
	s_cmp_eq_u32 s70, 11
	s_mov_b64 s[4:5], 0
	s_cselect_b64 s[2:3], -1, 0
	s_branch .LBB0_430

;     __device__ __forceinline__ void fused(f32x4 (&acc)[2][2][4][2], const GUnit& u, int wr, int wc, int fr, int fq, LAS unsigned char* lds, int wid, int lane) const {
;         const int rl0 = wr * 64 + fr, cl0 = wc * 32 + 8 * fq, grow0 = u.pm * 256 + rl0, gcol0 = u.pn * 256 + cl0;
;         f16* H16 = (f16*)(ws + WS_H16);
;         { u32x4 hw[2][4][2];
; #pragma unroll
;         for (int ai = 0; ai < 2; ++ai)
; #pragma unroll
;             for (int m = 0; m < 4; ++m)
; #pragma unroll
;                 for (int bj = 0; bj < 2; ++bj) hw[ai][m][bj] = *(const u32x4*)(H16 + (size_t)(grow0 + ai * 128 + m * 16) * 1024 + gcol0 + bj * 128);
;         asm volatile("" ::: "memory");
; #pragma unroll
;         for (int ai = 0; ai < 2; ++ai)
; #pragma unroll
;             for (int m = 0; m < 4; ++m) {
; #pragma unroll
;                 for (int bj = 0; bj < 2; ++bj) { f32x4 h0, h1; unpk8(hw[ai][m][bj], h0, h1);
;                     acc[ai][bj][m][0] += ALPHA * h0; acc[ai][bj][m][1] += ALPHA * h1;
.LBB0_432:
	s_andn2_b64 vcc, exec, s[2:3]
	s_cbranch_vccnz .LBB0_567
	v_mbcnt_lo_u32_b32 v32, -1, 0
	v_mbcnt_hi_u32_b32 v32, -1, v32
	s_lshl_b32 s2, s34, 8
	v_ashrrev_i32_e32 v34, 1, v32
	v_readlane_b32 s3, v251, 28
	v_and_or_b32 v233, v32, 15, s48
	v_and_b32_e32 v34, -8, v34
	s_lshl_b32 s14, s37, 8
	s_or_b32 s2, s2, s3
	v_add_u32_e32 v214, s14, v233
	v_add_u32_e32 v198, s2, v34
	v_readlane_b32 s2, v253, 4
	v_ashrrev_i32_e32 v199, 31, v198
	v_readlane_b32 s3, v253, 5
	v_ashrrev_i32_e32 v215, 31, v214
	v_lshlrev_b64 v[216:217], 11, v[214:215]
	v_lshl_add_u64 v[136:137], v[198:199], 1, s[2:3]
	v_lshl_add_u64 v[34:35], v[136:137], 0, v[216:217]
	global_load_dwordx4 v[192:195], v[34:35], off
	global_load_dwordx4 v[188:191], v[34:35], off offset:256
	v_or_b32_e32 v34, 16, v214
	v_ashrrev_i32_e32 v35, 31, v34
	v_lshlrev_b64 v[34:35], 11, v[34:35]
	v_lshl_add_u64 v[34:35], v[136:137], 0, v[34:35]
	global_load_dwordx4 v[184:187], v[34:35], off
	global_load_dwordx4 v[180:183], v[34:35], off offset:256
	v_or_b32_e32 v34, 32, v214
	v_ashrrev_i32_e32 v35, 31, v34
	v_lshlrev_b64 v[34:35], 11, v[34:35]
	v_lshl_add_u64 v[34:35], v[136:137], 0, v[34:35]
	global_load_dwordx4 v[176:179], v[34:35], off
	global_load_dwordx4 v[172:175], v[34:35], off offset:256
	v_or_b32_e32 v34, 48, v214
	v_ashrrev_i32_e32 v35, 31, v34
	v_lshlrev_b64 v[34:35], 11, v[34:35]
	v_lshl_add_u64 v[34:35], v[136:137], 0, v[34:35]
	global_load_dwordx4 v[168:171], v[34:35], off
	global_load_dwordx4 v[164:167], v[34:35], off offset:256
	v_add_u32_e32 v212, 0x80, v214
	v_ashrrev_i32_e32 v213, 31, v212
	v_lshlrev_b64 v[210:211], 11, v[212:213]
	v_lshl_add_u64 v[34:35], v[136:137], 0, v[210:211]
	global_load_dwordx4 v[160:163], v[34:35], off
	global_load_dwordx4 v[156:159], v[34:35], off offset:256
	v_add_u32_e32 v208, 0x90, v214
	v_ashrrev_i32_e32 v209, 31, v208
	v_lshlrev_b64 v[34:35], 11, v[208:209]
	v_lshl_add_u64 v[132:133], v[136:137], 0, v[34:35]
	global_load_dwordx4 v[152:155], v[132:133], off
	global_load_dwordx4 v[144:147], v[132:133], off offset:256
	v_add_u32_e32 v206, 0xa0, v214
	v_ashrrev_i32_e32 v207, 31, v206
	v_lshlrev_b64 v[204:205], 11, v[206:207]
	v_lshl_add_u64 v[132:133], v[136:137], 0, v[204:205]
	global_load_dwordx4 v[140:143], v[132:133], off
	s_nop 0
	global_load_dwordx4 v[132:135], v[132:133], off offset:256
	v_add_u32_e32 v200, 0xb0, v214
	v_ashrrev_i32_e32 v201, 31, v200
	v_lshlrev_b64 v[202:203], 11, v[200:201]
	v_lshl_add_u64 v[136:137], v[136:137], 0, v[202:203]
	global_load_dwordx4 v[148:151], v[136:137], off
	s_nop 0
	global_load_dwordx4 v[136:139], v[136:137], off offset:256
	s_waitcnt vmcnt(16)
	s_barrier
	s_mov_b32 s2, 0x3fd744fd
	v_mov_b32_e32 v226, 0x5800
	v_cmp_gt_u32_e32 vcc, 16, v32
	s_waitcnt vmcnt(0)
	v_cvt_f32_f16_e32 v234, v192
	v_cvt_f32_f16_sdwa v235, v192 dst_sel:DWORD dst_unused:UNUSED_PAD src0_sel:WORD_1
	v_cvt_f32_f16_e32 v192, v193
	v_cvt_f32_f16_sdwa v193, v193 dst_sel:DWORD dst_unused:UNUSED_PAD src0_sel:WORD_1
	v_cvt_f32_f16_e32 v236, v194
	v_cvt_f32_f16_sdwa v237, v194 dst_sel:DWORD dst_unused:UNUSED_PAD src0_sel:WORD_1
	v_cvt_f32_f16_e32 v194, v195
	v_cvt_f32_f16_sdwa v195, v195 dst_sel:DWORD dst_unused:UNUSED_PAD src0_sel:WORD_1
	v_pk_fma_f32 v[130:131], v[192:193], s[2:3], v[130:131] op_sel_hi:[1,0,1]
	v_cvt_f32_f16_e32 v192, v188
	v_cvt_f32_f16_sdwa v193, v188 dst_sel:DWORD dst_unused:UNUSED_PAD src0_sel:WORD_1
	v_pk_fma_f32 v[126:127], v[194:195], s[2:3], v[126:127] op_sel_hi:[1,0,1]
	v_cvt_f32_f16_e32 v188, v189
	v_cvt_f32_f16_sdwa v189, v189 dst_sel:DWORD dst_unused:UNUSED_PAD src0_sel:WORD_1
	v_cvt_f32_f16_e32 v194, v190
	v_cvt_f32_f16_sdwa v195, v190 dst_sel:DWORD dst_unused:UNUSED_PAD src0_sel:WORD_1
	v_cvt_f32_f16_e32 v190, v191
	v_cvt_f32_f16_sdwa v191, v191 dst_sel:DWORD dst_unused:UNUSED_PAD src0_sel:WORD_1
	v_pk_fma_f32 v[122:123], v[188:189], s[2:3], v[122:123] op_sel_hi:[1,0,1]
	v_cvt_f32_f16_e32 v188, v184
	v_cvt_f32_f16_sdwa v189, v184 dst_sel:DWORD dst_unused:UNUSED_PAD src0_sel:WORD_1
	v_pk_fma_f32 v[118:119], v[190:191], s[2:3], v[118:119] op_sel_hi:[1,0,1]
	v_cvt_f32_f16_e32 v184, v185
	v_cvt_f32_f16_sdwa v185, v185 dst_sel:DWORD dst_unused:UNUSED_PAD src0_sel:WORD_1
	v_cvt_f32_f16_e32 v190, v186
	v_cvt_f32_f16_sdwa v191, v186 dst_sel:DWORD dst_unused:UNUSED_PAD src0_sel:WORD_1
	v_cvt_f32_f16_e32 v186, v187
	v_cvt_f32_f16_sdwa v187, v187 dst_sel:DWORD dst_unused:UNUSED_PAD src0_sel:WORD_1
	v_pk_fma_f32 v[114:115], v[184:185], s[2:3], v[114:115] op_sel_hi:[1,0,1]
	v_cvt_f32_f16_e32 v184, v180
	v_cvt_f32_f16_sdwa v185, v180 dst_sel:DWORD dst_unused:UNUSED_PAD src0_sel:WORD_1
	v_pk_fma_f32 v[110:111], v[186:187], s[2:3], v[110:111] op_sel_hi:[1,0,1]
	v_cvt_f32_f16_e32 v180, v181
	v_cvt_f32_f16_sdwa v181, v181 dst_sel:DWORD dst_unused:UNUSED_PAD src0_sel:WORD_1
	v_cvt_f32_f16_e32 v186, v182
	v_cvt_f32_f16_sdwa v187, v182 dst_sel:DWORD dst_unused:UNUSED_PAD src0_sel:WORD_1
	v_cvt_f32_f16_e32 v182, v183
	v_cvt_f32_f16_sdwa v183, v183 dst_sel:DWORD dst_unused:UNUSED_PAD src0_sel:WORD_1
	v_pk_fma_f32 v[106:107], v[180:181], s[2:3], v[106:107] op_sel_hi:[1,0,1]
	v_cvt_f32_f16_e32 v180, v176
	v_cvt_f32_f16_sdwa v181, v176 dst_sel:DWORD dst_unused:UNUSED_PAD src0_sel:WORD_1
	v_pk_fma_f32 v[102:103], v[182:183], s[2:3], v[102:103] op_sel_hi:[1,0,1]
	v_cvt_f32_f16_e32 v176, v177
	v_cvt_f32_f16_sdwa v177, v177 dst_sel:DWORD dst_unused:UNUSED_PAD src0_sel:WORD_1
	v_cvt_f32_f16_e32 v182, v178
	v_cvt_f32_f16_sdwa v183, v178 dst_sel:DWORD dst_unused:UNUSED_PAD src0_sel:WORD_1
	v_cvt_f32_f16_e32 v178, v179
	v_cvt_f32_f16_sdwa v179, v179 dst_sel:DWORD dst_unused:UNUSED_PAD src0_sel:WORD_1
	v_pk_fma_f32 v[98:99], v[176:177], s[2:3], v[98:99] op_sel_hi:[1,0,1]
;     __device__ __forceinline__ void fused(f32x4 (&acc)[2][2][4][2], const GUnit& u, int wr, int wc, int fr, int fq, LAS unsigned char* lds, int wid, int lane) const {
;     ...
;         for (int ai = 0; ai < 2; ++ai)
; #pragma unroll
;             for (int m = 0; m < 4; ++m) {
; #pragma unroll
;                 for (int bj = 0; bj < 2; ++bj) { f32x4 h0, h1; unpk8(hw[ai][m][bj], h0, h1);
;                     acc[ai][bj][m][0] += ALPHA * h0; acc[ai][bj][m][1] += ALPHA * h1;
;                 }
;                 asm volatile("" : "+v"(acc[ai][0][m][0]), "+v"(acc[ai][0][m][1]), "+v"(acc[ai][1][m][0]), "+v"(acc[ai][1][m][1])); } }
	v_cvt_f32_f16_e32 v176, v172
	v_cvt_f32_f16_sdwa v177, v172 dst_sel:DWORD dst_unused:UNUSED_PAD src0_sel:WORD_1
	v_pk_fma_f32 v[94:95], v[178:179], s[2:3], v[94:95] op_sel_hi:[1,0,1]
	v_cvt_f32_f16_e32 v172, v173
	v_cvt_f32_f16_sdwa v173, v173 dst_sel:DWORD dst_unused:UNUSED_PAD src0_sel:WORD_1
	v_cvt_f32_f16_e32 v178, v174
	v_cvt_f32_f16_sdwa v179, v174 dst_sel:DWORD dst_unused:UNUSED_PAD src0_sel:WORD_1
	v_cvt_f32_f16_e32 v174, v175
	v_cvt_f32_f16_sdwa v175, v175 dst_sel:DWORD dst_unused:UNUSED_PAD src0_sel:WORD_1
	v_pk_fma_f32 v[90:91], v[172:173], s[2:3], v[90:91] op_sel_hi:[1,0,1]
	v_cvt_f32_f16_e32 v172, v168
	v_cvt_f32_f16_sdwa v173, v168 dst_sel:DWORD dst_unused:UNUSED_PAD src0_sel:WORD_1
	v_pk_fma_f32 v[86:87], v[174:175], s[2:3], v[86:87] op_sel_hi:[1,0,1]
	v_cvt_f32_f16_e32 v168, v169
	v_cvt_f32_f16_sdwa v169, v169 dst_sel:DWORD dst_unused:UNUSED_PAD src0_sel:WORD_1
	v_cvt_f32_f16_e32 v174, v170
	v_cvt_f32_f16_sdwa v175, v170 dst_sel:DWORD dst_unused:UNUSED_PAD src0_sel:WORD_1
	v_cvt_f32_f16_e32 v170, v171
	v_cvt_f32_f16_sdwa v171, v171 dst_sel:DWORD dst_unused:UNUSED_PAD src0_sel:WORD_1
	v_pk_fma_f32 v[82:83], v[168:169], s[2:3], v[82:83] op_sel_hi:[1,0,1]
	v_cvt_f32_f16_e32 v168, v164
	v_cvt_f32_f16_sdwa v169, v164 dst_sel:DWORD dst_unused:UNUSED_PAD src0_sel:WORD_1
	v_pk_fma_f32 v[78:79], v[170:171], s[2:3], v[78:79] op_sel_hi:[1,0,1]
	v_cvt_f32_f16_e32 v164, v165
	v_cvt_f32_f16_sdwa v165, v165 dst_sel:DWORD dst_unused:UNUSED_PAD src0_sel:WORD_1
	v_cvt_f32_f16_e32 v170, v166
	v_cvt_f32_f16_sdwa v171, v166 dst_sel:DWORD dst_unused:UNUSED_PAD src0_sel:WORD_1
	v_cvt_f32_f16_e32 v166, v167
	v_cvt_f32_f16_sdwa v167, v167 dst_sel:DWORD dst_unused:UNUSED_PAD src0_sel:WORD_1
	v_pk_fma_f32 v[74:75], v[164:165], s[2:3], v[74:75] op_sel_hi:[1,0,1]
	v_cvt_f32_f16_e32 v164, v160
	v_cvt_f32_f16_sdwa v165, v160 dst_sel:DWORD dst_unused:UNUSED_PAD src0_sel:WORD_1
	v_pk_fma_f32 v[70:71], v[166:167], s[2:3], v[70:71] op_sel_hi:[1,0,1]
	v_cvt_f32_f16_e32 v160, v161
	v_cvt_f32_f16_sdwa v161, v161 dst_sel:DWORD dst_unused:UNUSED_PAD src0_sel:WORD_1
	v_cvt_f32_f16_e32 v166, v162
	v_cvt_f32_f16_sdwa v167, v162 dst_sel:DWORD dst_unused:UNUSED_PAD src0_sel:WORD_1
	v_cvt_f32_f16_e32 v162, v163
	v_cvt_f32_f16_sdwa v163, v163 dst_sel:DWORD dst_unused:UNUSED_PAD src0_sel:WORD_1
	v_pk_fma_f32 v[66:67], v[160:161], s[2:3], v[66:67] op_sel_hi:[1,0,1]
	v_cvt_f32_f16_e32 v160, v156
	v_cvt_f32_f16_sdwa v161, v156 dst_sel:DWORD dst_unused:UNUSED_PAD src0_sel:WORD_1
	v_pk_fma_f32 v[62:63], v[162:163], s[2:3], v[62:63] op_sel_hi:[1,0,1]
	v_cvt_f32_f16_e32 v156, v157
	v_cvt_f32_f16_sdwa v157, v157 dst_sel:DWORD dst_unused:UNUSED_PAD src0_sel:WORD_1
	v_cvt_f32_f16_e32 v162, v158
	v_cvt_f32_f16_sdwa v163, v158 dst_sel:DWORD dst_unused:UNUSED_PAD src0_sel:WORD_1
	v_cvt_f32_f16_e32 v158, v159
	v_cvt_f32_f16_sdwa v159, v159 dst_sel:DWORD dst_unused:UNUSED_PAD src0_sel:WORD_1
	v_pk_fma_f32 v[58:59], v[156:157], s[2:3], v[58:59] op_sel_hi:[1,0,1]
	v_cvt_f32_f16_e32 v156, v152
	v_cvt_f32_f16_sdwa v157, v152 dst_sel:DWORD dst_unused:UNUSED_PAD src0_sel:WORD_1
	v_pk_fma_f32 v[54:55], v[158:159], s[2:3], v[54:55] op_sel_hi:[1,0,1]
	v_cvt_f32_f16_e32 v152, v153
	v_cvt_f32_f16_sdwa v153, v153 dst_sel:DWORD dst_unused:UNUSED_PAD src0_sel:WORD_1
	v_cvt_f32_f16_e32 v158, v154
	v_cvt_f32_f16_sdwa v159, v154 dst_sel:DWORD dst_unused:UNUSED_PAD src0_sel:WORD_1
	v_cvt_f32_f16_e32 v154, v155
	v_cvt_f32_f16_sdwa v155, v155 dst_sel:DWORD dst_unused:UNUSED_PAD src0_sel:WORD_1
	v_pk_fma_f32 v[50:51], v[152:153], s[2:3], v[50:51] op_sel_hi:[1,0,1]
	v_cvt_f32_f16_e32 v152, v144
	v_cvt_f32_f16_sdwa v153, v144 dst_sel:DWORD dst_unused:UNUSED_PAD src0_sel:WORD_1
	v_pk_fma_f32 v[46:47], v[154:155], s[2:3], v[46:47] op_sel_hi:[1,0,1]
	v_cvt_f32_f16_e32 v144, v145
	v_cvt_f32_f16_sdwa v145, v145 dst_sel:DWORD dst_unused:UNUSED_PAD src0_sel:WORD_1
	v_cvt_f32_f16_e32 v154, v146
	v_cvt_f32_f16_sdwa v155, v146 dst_sel:DWORD dst_unused:UNUSED_PAD src0_sel:WORD_1
	v_cvt_f32_f16_e32 v146, v147
	v_cvt_f32_f16_sdwa v147, v147 dst_sel:DWORD dst_unused:UNUSED_PAD src0_sel:WORD_1
	v_pk_fma_f32 v[42:43], v[144:145], s[2:3], v[42:43] op_sel_hi:[1,0,1]
	v_cvt_f32_f16_e32 v144, v140
	v_cvt_f32_f16_sdwa v145, v140 dst_sel:DWORD dst_unused:UNUSED_PAD src0_sel:WORD_1
	v_pk_fma_f32 v[38:39], v[146:147], s[2:3], v[38:39] op_sel_hi:[1,0,1]
	v_cvt_f32_f16_e32 v140, v141
	v_cvt_f32_f16_sdwa v141, v141 dst_sel:DWORD dst_unused:UNUSED_PAD src0_sel:WORD_1
	v_cvt_f32_f16_e32 v146, v142
	v_cvt_f32_f16_sdwa v147, v142 dst_sel:DWORD dst_unused:UNUSED_PAD src0_sel:WORD_1
	v_cvt_f32_f16_e32 v142, v143
	v_cvt_f32_f16_sdwa v143, v143 dst_sel:DWORD dst_unused:UNUSED_PAD src0_sel:WORD_1
	v_pk_fma_f32 v[30:31], v[140:141], s[2:3], v[30:31] op_sel_hi:[1,0,1]
	v_cvt_f32_f16_e32 v140, v132
	v_cvt_f32_f16_sdwa v141, v132 dst_sel:DWORD dst_unused:UNUSED_PAD src0_sel:WORD_1
	v_pk_fma_f32 v[26:27], v[142:143], s[2:3], v[26:27] op_sel_hi:[1,0,1]
	v_cvt_f32_f16_e32 v132, v133
	v_cvt_f32_f16_sdwa v133, v133 dst_sel:DWORD dst_unused:UNUSED_PAD src0_sel:WORD_1
	v_cvt_f32_f16_e32 v142, v134
	v_cvt_f32_f16_sdwa v143, v134 dst_sel:DWORD dst_unused:UNUSED_PAD src0_sel:WORD_1
	v_cvt_f32_f16_e32 v134, v135
	v_cvt_f32_f16_sdwa v135, v135 dst_sel:DWORD dst_unused:UNUSED_PAD src0_sel:WORD_1
	v_pk_fma_f32 v[22:23], v[132:133], s[2:3], v[22:23] op_sel_hi:[1,0,1]
	v_cvt_f32_f16_e32 v132, v148
	v_cvt_f32_f16_sdwa v133, v148 dst_sel:DWORD dst_unused:UNUSED_PAD src0_sel:WORD_1
	v_pk_fma_f32 v[18:19], v[134:135], s[2:3], v[18:19] op_sel_hi:[1,0,1]
	v_cvt_f32_f16_e32 v134, v149
	v_cvt_f32_f16_sdwa v135, v149 dst_sel:DWORD dst_unused:UNUSED_PAD src0_sel:WORD_1
; #define LAS __attribute__((address_space(3)))
; __device__ __forceinline__ float shx(float v, int mask) { return __builtin_bit_cast(float, __builtin_amdgcn_ds_bpermute((lane_now() ^ mask) << 2, __builtin_bit_cast(int, v))); }
;     __device__ __forceinline__ void fused(f32x4 (&acc)[2][2][4][2], const GUnit& u, int wr, int wc, int fr, int fq, LAS unsigned char* lds, int wid, int lane) const {
;     ...
;                 for (int bj = 0; bj < 2; ++bj) { f32x4 h0, h1; unpk8(hw[ai][m][bj], h0, h1);
;                     acc[ai][bj][m][0] += ALPHA * h0; acc[ai][bj][m][1] += ALPHA * h1;
;                 }
;                 asm volatile("" : "+v"(acc[ai][0][m][0]), "+v"(acc[ai][0][m][1]), "+v"(acc[ai][1][m][0]), "+v"(acc[ai][1][m][1])); } }
;         LAS f32x2* P = (LAS f32x2*)lds; LAS f32x2* S = (LAS f32x2*)(lds + 8192); LAS unsigned* flag = (LAS unsigned*)(lds + 8192 + 2048);
;         unsigned* xbuf = (unsigned*)(ws + WS_X); unsigned* tmo = (unsigned*)(ws + WS_CTL) + CW_TMO;
; #pragma unroll
;         for (int ai = 0; ai < 2; ++ai)
; #pragma unroll
;             for (int m = 0; m < 4; ++m) {
;                 float s = 0.f;
; #pragma unroll
;                 for (int bj = 0; bj < 2; ++bj)
; #pragma unroll
;                     for (int n = 0; n < 2; ++n) { const f32x4 x = acc[ai][bj][m][n]; s += (x[0] + x[1]) + (x[2] + x[3]); }
;                 s += shx(s, 16); s += shx(s, 32);
;                 const float mw = s * (1.0f / 64.0f); float q = 0.f;
	v_pk_fma_f32 v[12:13], v[132:133], s[2:3], v[12:13] op_sel_hi:[1,0,1]
	v_cvt_f32_f16_e32 v132, v136
	v_cvt_f32_f16_sdwa v133, v136 dst_sel:DWORD dst_unused:UNUSED_PAD src0_sel:WORD_1
	v_pk_fma_f32 v[14:15], v[134:135], s[2:3], v[14:15] op_sel_hi:[1,0,1]
	v_cvt_f32_f16_e32 v134, v137
	v_cvt_f32_f16_sdwa v135, v137 dst_sel:DWORD dst_unused:UNUSED_PAD src0_sel:WORD_1
	v_cvt_f32_f16_e32 v136, v138
	v_cvt_f32_f16_sdwa v137, v138 dst_sel:DWORD dst_unused:UNUSED_PAD src0_sel:WORD_1
	v_pk_fma_f32 v[128:129], v[234:235], s[2:3], v[128:129] op_sel_hi:[1,0,1]
	v_pk_fma_f32 v[124:125], v[236:237], s[2:3], v[124:125] op_sel_hi:[1,0,1]
	v_pk_fma_f32 v[120:121], v[192:193], s[2:3], v[120:121] op_sel_hi:[1,0,1]
	v_pk_fma_f32 v[116:117], v[194:195], s[2:3], v[116:117] op_sel_hi:[1,0,1]
	v_cvt_f32_f16_e32 v138, v139
	v_cvt_f32_f16_sdwa v139, v139 dst_sel:DWORD dst_unused:UNUSED_PAD src0_sel:WORD_1
	v_pk_fma_f32 v[6:7], v[134:135], s[2:3], v[6:7] op_sel_hi:[1,0,1]
	v_pk_fma_f32 v[4:5], v[132:133], s[2:3], v[4:5] op_sel_hi:[1,0,1]
	v_pk_fma_f32 v[0:1], v[136:137], s[2:3], v[0:1] op_sel_hi:[1,0,1]
	v_pk_fma_f32 v[20:21], v[140:141], s[2:3], v[20:21] op_sel_hi:[1,0,1]
	v_pk_fma_f32 v[16:17], v[142:143], s[2:3], v[16:17] op_sel_hi:[1,0,1]
	v_cvt_f32_f16_e32 v140, v150
	v_cvt_f32_f16_sdwa v141, v150 dst_sel:DWORD dst_unused:UNUSED_PAD src0_sel:WORD_1
	v_cvt_f32_f16_e32 v142, v151
	v_cvt_f32_f16_sdwa v143, v151 dst_sel:DWORD dst_unused:UNUSED_PAD src0_sel:WORD_1
	v_pk_fma_f32 v[2:3], v[138:139], s[2:3], v[2:3] op_sel_hi:[1,0,1]
	v_pk_fma_f32 v[112:113], v[188:189], s[2:3], v[112:113] op_sel_hi:[1,0,1]
	v_pk_fma_f32 v[108:109], v[190:191], s[2:3], v[108:109] op_sel_hi:[1,0,1]
	v_pk_fma_f32 v[104:105], v[184:185], s[2:3], v[104:105] op_sel_hi:[1,0,1]
	v_pk_fma_f32 v[100:101], v[186:187], s[2:3], v[100:101] op_sel_hi:[1,0,1]
	v_pk_fma_f32 v[96:97], v[180:181], s[2:3], v[96:97] op_sel_hi:[1,0,1]
	v_pk_fma_f32 v[92:93], v[182:183], s[2:3], v[92:93] op_sel_hi:[1,0,1]
	v_pk_fma_f32 v[88:89], v[176:177], s[2:3], v[88:89] op_sel_hi:[1,0,1]
	v_pk_fma_f32 v[84:85], v[178:179], s[2:3], v[84:85] op_sel_hi:[1,0,1]
	v_pk_fma_f32 v[80:81], v[172:173], s[2:3], v[80:81] op_sel_hi:[1,0,1]
	v_pk_fma_f32 v[76:77], v[174:175], s[2:3], v[76:77] op_sel_hi:[1,0,1]
	v_pk_fma_f32 v[72:73], v[168:169], s[2:3], v[72:73] op_sel_hi:[1,0,1]
	v_pk_fma_f32 v[68:69], v[170:171], s[2:3], v[68:69] op_sel_hi:[1,0,1]
	v_pk_fma_f32 v[64:65], v[164:165], s[2:3], v[64:65] op_sel_hi:[1,0,1]
	v_pk_fma_f32 v[60:61], v[166:167], s[2:3], v[60:61] op_sel_hi:[1,0,1]
	v_pk_fma_f32 v[56:57], v[160:161], s[2:3], v[56:57] op_sel_hi:[1,0,1]
	v_pk_fma_f32 v[52:53], v[162:163], s[2:3], v[52:53] op_sel_hi:[1,0,1]
	v_pk_fma_f32 v[48:49], v[156:157], s[2:3], v[48:49] op_sel_hi:[1,0,1]
	v_pk_fma_f32 v[44:45], v[158:159], s[2:3], v[44:45] op_sel_hi:[1,0,1]
	v_pk_fma_f32 v[40:41], v[152:153], s[2:3], v[40:41] op_sel_hi:[1,0,1]
	v_pk_fma_f32 v[36:37], v[154:155], s[2:3], v[36:37] op_sel_hi:[1,0,1]
	v_pk_fma_f32 v[28:29], v[144:145], s[2:3], v[28:29] op_sel_hi:[1,0,1]
	v_pk_fma_f32 v[24:25], v[146:147], s[2:3], v[24:25] op_sel_hi:[1,0,1]
	v_pk_fma_f32 v[10:11], v[142:143], s[2:3], v[10:11] op_sel_hi:[1,0,1]
	v_pk_fma_f32 v[8:9], v[140:141], s[2:3], v[8:9] op_sel_hi:[1,0,1]
	v_readlane_b32 s2, v252, 13
	v_cmp_gt_u32_e32 vcc, 16, v32
	v_pk_add_f32 v[136:137], v[128:129], v[130:131]
	v_pk_add_f32 v[150:151], v[112:113], v[114:115]
	v_pk_add_f32 v[164:165], v[96:97], v[98:99]
	v_pk_add_f32 v[178:179], v[80:81], v[82:83]
	v_pk_add_f32 v[138:139], v[124:125], v[126:127]
	v_pk_add_f32 v[152:153], v[108:109], v[110:111]
	v_pk_add_f32 v[166:167], v[92:93], v[94:95]
	v_pk_add_f32 v[180:181], v[76:77], v[78:79]
	v_pk_add_f32 v[140:141], v[120:121], v[122:123]
	v_pk_add_f32 v[154:155], v[104:105], v[106:107]
	v_pk_add_f32 v[168:169], v[88:89], v[90:91]
	v_pk_add_f32 v[182:183], v[72:73], v[74:75]
	v_pk_add_f32 v[142:143], v[116:117], v[118:119]
	v_pk_add_f32 v[156:157], v[100:101], v[102:103]
	v_pk_add_f32 v[170:171], v[84:85], v[86:87]
	v_pk_add_f32 v[184:185], v[68:69], v[70:71]
	v_pk_add_f32 v[136:137], v[136:137], v[138:139]
	v_pk_add_f32 v[150:151], v[150:151], v[152:153]
	v_pk_add_f32 v[164:165], v[164:165], v[166:167]
	v_pk_add_f32 v[178:179], v[178:179], v[180:181]
	v_pk_add_f32 v[140:141], v[140:141], v[142:143]
	v_pk_add_f32 v[154:155], v[154:155], v[156:157]
	v_pk_add_f32 v[168:169], v[168:169], v[170:171]
	v_pk_add_f32 v[182:183], v[182:183], v[184:185]
	v_pk_add_f32 v[136:137], v[136:137], v[140:141]
	v_pk_add_f32 v[150:151], v[150:151], v[154:155]
	v_pk_add_f32 v[164:165], v[164:165], v[168:169]
	v_pk_add_f32 v[178:179], v[178:179], v[182:183]
	v_add_f32_e32 v145, v136, v137
	v_add_f32_e32 v159, v150, v151
	v_add_f32_e32 v173, v164, v165
	v_add_f32_e32 v187, v178, v179
	v_mov_b32_e32 v148, v145
	v_mov_b32_e32 v162, v159
	v_mov_b32_e32 v176, v173
	v_mov_b32_e32 v190, v187
	v_permlane16_swap_b32 v148, v145
	v_permlane16_swap_b32 v162, v159
	v_permlane16_swap_b32 v176, v173
	v_permlane16_swap_b32 v190, v187
	v_add_f32_e32 v145, v145, v148
	v_add_f32_e32 v159, v159, v162
	v_add_f32_e32 v173, v173, v176
	v_add_f32_e32 v187, v187, v190
	v_mov_b32_e32 v148, v145
	v_mov_b32_e32 v162, v159
	v_mov_b32_e32 v176, v173
	v_mov_b32_e32 v190, v187
	v_permlane32_swap_b32 v148, v145
	v_permlane32_swap_b32 v162, v159
	v_permlane32_swap_b32 v176, v173
	v_permlane32_swap_b32 v190, v187
	v_add_f32_e32 v145, v145, v148
	v_add_f32_e32 v159, v159, v162
	v_add_f32_e32 v173, v173, v176
	v_add_f32_e32 v187, v187, v190
	v_mul_f32_e32 v144, 0x3c800000, v145
	v_mul_f32_e32 v158, 0x3c800000, v159
	v_mul_f32_e32 v172, 0x3c800000, v173
; __device__ __forceinline__ float shx(float v, int mask) { return __builtin_bit_cast(float, __builtin_amdgcn_ds_bpermute((lane_now() ^ mask) << 2, __builtin_bit_cast(int, v))); }
;     __device__ __forceinline__ void fused(f32x4 (&acc)[2][2][4][2], const GUnit& u, int wr, int wc, int fr, int fq, LAS unsigned char* lds, int wid, int lane) const {
;     ...
;                 const float mw = s * (1.0f / 64.0f); float q = 0.f;
; #pragma unroll
;                 for (int bj = 0; bj < 2; ++bj)
; #pragma unroll
;                     for (int n = 0; n < 2; ++n) { const f32x4 d = acc[ai][bj][m][n] - mw; q += (d[0] * d[0] + d[1] * d[1]) + (d[2] * d[2] + d[3] * d[3]); }
;                 q += shx(q, 16); q += shx(q, 32);
	v_mul_f32_e32 v186, 0x3c800000, v187
	v_pk_add_f32 v[136:137], v[128:129], v[144:145] op_sel_hi:[1,0] neg_lo:[0,1] neg_hi:[0,1]
	v_pk_add_f32 v[150:151], v[112:113], v[158:159] op_sel_hi:[1,0] neg_lo:[0,1] neg_hi:[0,1]
	v_pk_add_f32 v[164:165], v[96:97], v[172:173] op_sel_hi:[1,0] neg_lo:[0,1] neg_hi:[0,1]
	v_pk_add_f32 v[178:179], v[80:81], v[186:187] op_sel_hi:[1,0] neg_lo:[0,1] neg_hi:[0,1]
	v_pk_mul_f32 v[146:147], v[136:137], v[136:137]
	v_pk_mul_f32 v[160:161], v[150:151], v[150:151]
	v_pk_mul_f32 v[174:175], v[164:165], v[164:165]
	v_pk_mul_f32 v[188:189], v[178:179], v[178:179]
	v_pk_add_f32 v[138:139], v[130:131], v[144:145] op_sel_hi:[1,0] neg_lo:[0,1] neg_hi:[0,1]
	v_pk_add_f32 v[152:153], v[114:115], v[158:159] op_sel_hi:[1,0] neg_lo:[0,1] neg_hi:[0,1]
	v_pk_add_f32 v[166:167], v[98:99], v[172:173] op_sel_hi:[1,0] neg_lo:[0,1] neg_hi:[0,1]
	v_pk_add_f32 v[180:181], v[82:83], v[186:187] op_sel_hi:[1,0] neg_lo:[0,1] neg_hi:[0,1]
	v_pk_fma_f32 v[146:147], v[138:139], v[138:139], v[146:147]
	v_pk_fma_f32 v[160:161], v[152:153], v[152:153], v[160:161]
	v_pk_fma_f32 v[174:175], v[166:167], v[166:167], v[174:175]
	v_pk_fma_f32 v[188:189], v[180:181], v[180:181], v[188:189]
	v_pk_add_f32 v[140:141], v[124:125], v[144:145] op_sel_hi:[1,0] neg_lo:[0,1] neg_hi:[0,1]
	v_pk_add_f32 v[154:155], v[108:109], v[158:159] op_sel_hi:[1,0] neg_lo:[0,1] neg_hi:[0,1]
	v_pk_add_f32 v[168:169], v[92:93], v[172:173] op_sel_hi:[1,0] neg_lo:[0,1] neg_hi:[0,1]
	v_pk_add_f32 v[182:183], v[76:77], v[186:187] op_sel_hi:[1,0] neg_lo:[0,1] neg_hi:[0,1]
	v_pk_fma_f32 v[146:147], v[140:141], v[140:141], v[146:147]
	v_pk_fma_f32 v[160:161], v[154:155], v[154:155], v[160:161]
	v_pk_fma_f32 v[174:175], v[168:169], v[168:169], v[174:175]
	v_pk_fma_f32 v[188:189], v[182:183], v[182:183], v[188:189]
	v_pk_add_f32 v[142:143], v[126:127], v[144:145] op_sel_hi:[1,0] neg_lo:[0,1] neg_hi:[0,1]
	v_pk_add_f32 v[156:157], v[110:111], v[158:159] op_sel_hi:[1,0] neg_lo:[0,1] neg_hi:[0,1]
	v_pk_add_f32 v[170:171], v[94:95], v[172:173] op_sel_hi:[1,0] neg_lo:[0,1] neg_hi:[0,1]
	v_pk_add_f32 v[184:185], v[78:79], v[186:187] op_sel_hi:[1,0] neg_lo:[0,1] neg_hi:[0,1]
	v_pk_fma_f32 v[146:147], v[142:143], v[142:143], v[146:147]
	v_pk_fma_f32 v[160:161], v[156:157], v[156:157], v[160:161]
	v_pk_fma_f32 v[174:175], v[170:171], v[170:171], v[174:175]
	v_pk_fma_f32 v[188:189], v[184:185], v[184:185], v[188:189]
	v_pk_add_f32 v[136:137], v[120:121], v[144:145] op_sel_hi:[1,0] neg_lo:[0,1] neg_hi:[0,1]
	v_pk_add_f32 v[150:151], v[104:105], v[158:159] op_sel_hi:[1,0] neg_lo:[0,1] neg_hi:[0,1]
	v_pk_add_f32 v[164:165], v[88:89], v[172:173] op_sel_hi:[1,0] neg_lo:[0,1] neg_hi:[0,1]
	v_pk_add_f32 v[178:179], v[72:73], v[186:187] op_sel_hi:[1,0] neg_lo:[0,1] neg_hi:[0,1]
	v_pk_fma_f32 v[146:147], v[136:137], v[136:137], v[146:147]
	v_pk_fma_f32 v[160:161], v[150:151], v[150:151], v[160:161]
	v_pk_fma_f32 v[174:175], v[164:165], v[164:165], v[174:175]
	v_pk_fma_f32 v[188:189], v[178:179], v[178:179], v[188:189]
	v_pk_add_f32 v[138:139], v[122:123], v[144:145] op_sel_hi:[1,0] neg_lo:[0,1] neg_hi:[0,1]
	v_pk_add_f32 v[152:153], v[106:107], v[158:159] op_sel_hi:[1,0] neg_lo:[0,1] neg_hi:[0,1]
	v_pk_add_f32 v[166:167], v[90:91], v[172:173] op_sel_hi:[1,0] neg_lo:[0,1] neg_hi:[0,1]
	v_pk_add_f32 v[180:181], v[74:75], v[186:187] op_sel_hi:[1,0] neg_lo:[0,1] neg_hi:[0,1]
	v_pk_fma_f32 v[146:147], v[138:139], v[138:139], v[146:147]
	v_pk_fma_f32 v[160:161], v[152:153], v[152:153], v[160:161]
	v_pk_fma_f32 v[174:175], v[166:167], v[166:167], v[174:175]
	v_pk_fma_f32 v[188:189], v[180:181], v[180:181], v[188:189]
	v_pk_add_f32 v[140:141], v[116:117], v[144:145] op_sel_hi:[1,0] neg_lo:[0,1] neg_hi:[0,1]
	v_pk_add_f32 v[154:155], v[100:101], v[158:159] op_sel_hi:[1,0] neg_lo:[0,1] neg_hi:[0,1]
	v_pk_add_f32 v[168:169], v[84:85], v[172:173] op_sel_hi:[1,0] neg_lo:[0,1] neg_hi:[0,1]
	v_pk_add_f32 v[182:183], v[68:69], v[186:187] op_sel_hi:[1,0] neg_lo:[0,1] neg_hi:[0,1]
	v_pk_fma_f32 v[146:147], v[140:141], v[140:141], v[146:147]
	v_pk_fma_f32 v[160:161], v[154:155], v[154:155], v[160:161]
	v_pk_fma_f32 v[174:175], v[168:169], v[168:169], v[174:175]
	v_pk_fma_f32 v[188:189], v[182:183], v[182:183], v[188:189]
	v_pk_add_f32 v[142:143], v[118:119], v[144:145] op_sel_hi:[1,0] neg_lo:[0,1] neg_hi:[0,1]
	v_pk_add_f32 v[156:157], v[102:103], v[158:159] op_sel_hi:[1,0] neg_lo:[0,1] neg_hi:[0,1]
	v_pk_add_f32 v[170:171], v[86:87], v[172:173] op_sel_hi:[1,0] neg_lo:[0,1] neg_hi:[0,1]
	v_pk_add_f32 v[184:185], v[70:71], v[186:187] op_sel_hi:[1,0] neg_lo:[0,1] neg_hi:[0,1]
	v_pk_fma_f32 v[146:147], v[142:143], v[142:143], v[146:147]
	v_pk_fma_f32 v[160:161], v[156:157], v[156:157], v[160:161]
	v_pk_fma_f32 v[174:175], v[170:171], v[170:171], v[174:175]
	v_pk_fma_f32 v[188:189], v[184:185], v[184:185], v[188:189]
	v_add_f32_e32 v145, v146, v147
	v_add_f32_e32 v159, v160, v161
	v_add_f32_e32 v173, v174, v175
	v_add_f32_e32 v187, v188, v189
	v_mov_b32_e32 v148, v145
	v_mov_b32_e32 v162, v159
	v_mov_b32_e32 v176, v173
	v_mov_b32_e32 v190, v187
	v_permlane16_swap_b32 v148, v145
	v_permlane16_swap_b32 v162, v159
	v_permlane16_swap_b32 v176, v173
	v_permlane16_swap_b32 v190, v187
	v_add_f32_e32 v145, v145, v148
	v_add_f32_e32 v159, v159, v162
	v_add_f32_e32 v173, v173, v176
	v_add_f32_e32 v187, v187, v190
	v_mov_b32_e32 v148, v145
	v_mov_b32_e32 v162, v159
	v_mov_b32_e32 v176, v173
	v_mov_b32_e32 v190, v187
	v_permlane32_swap_b32 v148, v145
	v_permlane32_swap_b32 v162, v159
	v_permlane32_swap_b32 v176, v173
	v_permlane32_swap_b32 v190, v187
	v_add_f32_e32 v145, v145, v148
	v_add_f32_e32 v159, v159, v162
	v_add_f32_e32 v173, v173, v176
; __device__ __forceinline__ float shx(float v, int mask) { return __builtin_bit_cast(float, __builtin_amdgcn_ds_bpermute((lane_now() ^ mask) << 2, __builtin_bit_cast(int, v))); }
;     __device__ __forceinline__ void fused(f32x4 (&acc)[2][2][4][2], const GUnit& u, int wr, int wc, int fr, int fq, LAS unsigned char* lds, int wid, int lane) const {
;     ...
;                 float s = 0.f;
; #pragma unroll
;                 for (int bj = 0; bj < 2; ++bj)
; #pragma unroll
;                     for (int n = 0; n < 2; ++n) { const f32x4 x = acc[ai][bj][m][n]; s += (x[0] + x[1]) + (x[2] + x[3]); }
;                 s += shx(s, 16); s += shx(s, 32);
;                 const float mw = s * (1.0f / 64.0f); float q = 0.f;
; #pragma unroll
;                 for (int bj = 0; bj < 2; ++bj)
; #pragma unroll
;                     for (int n = 0; n < 2; ++n) { const f32x4 d = acc[ai][bj][m][n] - mw; q += (d[0] * d[0] + d[1] * d[1]) + (d[2] * d[2] + d[3] * d[3]); }
;                 q += shx(q, 16); q += shx(q, 32);
;                 if (fq == 0) P[(ai * 128 + wr * 64 + m * 16 + fr) * 4 + wc] = (f32x2){mw, q};
	v_add_f32_e32 v187, v187, v190
	v_lshl_add_u32 v132, v233, 5, s2
	s_and_saveexec_b64 s[4:5], vcc
	ds_write_b64 v132, v[144:145]
	ds_write_b64 v132, v[158:159] offset:512
	ds_write_b64 v132, v[172:173] offset:1024
	ds_write_b64 v132, v[186:187] offset:1536
	s_or_b64 exec, exec, s[4:5]
	v_pk_add_f32 v[136:137], v[64:65], v[66:67]
	v_pk_add_f32 v[150:151], v[48:49], v[50:51]
	v_pk_add_f32 v[164:165], v[28:29], v[30:31]
	v_pk_add_f32 v[178:179], v[12:13], v[14:15]
	v_pk_add_f32 v[138:139], v[60:61], v[62:63]
	v_pk_add_f32 v[152:153], v[44:45], v[46:47]
	v_pk_add_f32 v[166:167], v[24:25], v[26:27]
	v_pk_add_f32 v[180:181], v[8:9], v[10:11]
	v_pk_add_f32 v[140:141], v[56:57], v[58:59]
	v_pk_add_f32 v[154:155], v[40:41], v[42:43]
	v_pk_add_f32 v[168:169], v[20:21], v[22:23]
	v_pk_add_f32 v[182:183], v[4:5], v[6:7]
	v_pk_add_f32 v[142:143], v[52:53], v[54:55]
	v_pk_add_f32 v[156:157], v[36:37], v[38:39]
	v_pk_add_f32 v[170:171], v[16:17], v[18:19]
	v_pk_add_f32 v[184:185], v[0:1], v[2:3]
	v_pk_add_f32 v[136:137], v[136:137], v[138:139]
	v_pk_add_f32 v[150:151], v[150:151], v[152:153]
	v_pk_add_f32 v[164:165], v[164:165], v[166:167]
	v_pk_add_f32 v[178:179], v[178:179], v[180:181]
	v_pk_add_f32 v[140:141], v[140:141], v[142:143]
	v_pk_add_f32 v[154:155], v[154:155], v[156:157]
	v_pk_add_f32 v[168:169], v[168:169], v[170:171]
	v_pk_add_f32 v[182:183], v[182:183], v[184:185]
	v_pk_add_f32 v[136:137], v[136:137], v[140:141]
	v_pk_add_f32 v[150:151], v[150:151], v[154:155]
	v_pk_add_f32 v[164:165], v[164:165], v[168:169]
	v_pk_add_f32 v[178:179], v[178:179], v[182:183]
	v_add_f32_e32 v145, v136, v137
	v_add_f32_e32 v159, v150, v151
	v_add_f32_e32 v173, v164, v165
	v_add_f32_e32 v187, v178, v179
	v_mov_b32_e32 v148, v145
	v_mov_b32_e32 v162, v159
	v_mov_b32_e32 v176, v173
	v_mov_b32_e32 v190, v187
	v_permlane16_swap_b32 v148, v145
	v_permlane16_swap_b32 v162, v159
	v_permlane16_swap_b32 v176, v173
	v_permlane16_swap_b32 v190, v187
	v_add_f32_e32 v145, v145, v148
	v_add_f32_e32 v159, v159, v162
	v_add_f32_e32 v173, v173, v176
	v_add_f32_e32 v187, v187, v190
	v_mov_b32_e32 v148, v145
	v_mov_b32_e32 v162, v159
	v_mov_b32_e32 v176, v173
	v_mov_b32_e32 v190, v187
	v_permlane32_swap_b32 v148, v145
	v_permlane32_swap_b32 v162, v159
	v_permlane32_swap_b32 v176, v173
	v_permlane32_swap_b32 v190, v187
	v_add_f32_e32 v145, v145, v148
	v_add_f32_e32 v159, v159, v162
	v_add_f32_e32 v173, v173, v176
	v_add_f32_e32 v187, v187, v190
	v_mul_f32_e32 v144, 0x3c800000, v145
	v_mul_f32_e32 v158, 0x3c800000, v159
	v_mul_f32_e32 v172, 0x3c800000, v173
	v_mul_f32_e32 v186, 0x3c800000, v187
	v_pk_add_f32 v[136:137], v[64:65], v[144:145] op_sel_hi:[1,0] neg_lo:[0,1] neg_hi:[0,1]
	v_pk_add_f32 v[150:151], v[48:49], v[158:159] op_sel_hi:[1,0] neg_lo:[0,1] neg_hi:[0,1]
	v_pk_add_f32 v[164:165], v[28:29], v[172:173] op_sel_hi:[1,0] neg_lo:[0,1] neg_hi:[0,1]
	v_pk_add_f32 v[178:179], v[12:13], v[186:187] op_sel_hi:[1,0] neg_lo:[0,1] neg_hi:[0,1]
	v_pk_mul_f32 v[146:147], v[136:137], v[136:137]
	v_pk_mul_f32 v[160:161], v[150:151], v[150:151]
	v_pk_mul_f32 v[174:175], v[164:165], v[164:165]
	v_pk_mul_f32 v[188:189], v[178:179], v[178:179]
	v_pk_add_f32 v[138:139], v[66:67], v[144:145] op_sel_hi:[1,0] neg_lo:[0,1] neg_hi:[0,1]
	v_pk_add_f32 v[152:153], v[50:51], v[158:159] op_sel_hi:[1,0] neg_lo:[0,1] neg_hi:[0,1]
	v_pk_add_f32 v[166:167], v[30:31], v[172:173] op_sel_hi:[1,0] neg_lo:[0,1] neg_hi:[0,1]
	v_pk_add_f32 v[180:181], v[14:15], v[186:187] op_sel_hi:[1,0] neg_lo:[0,1] neg_hi:[0,1]
	v_pk_fma_f32 v[146:147], v[138:139], v[138:139], v[146:147]
	v_pk_fma_f32 v[160:161], v[152:153], v[152:153], v[160:161]
	v_pk_fma_f32 v[174:175], v[166:167], v[166:167], v[174:175]
	v_pk_fma_f32 v[188:189], v[180:181], v[180:181], v[188:189]
	v_pk_add_f32 v[140:141], v[60:61], v[144:145] op_sel_hi:[1,0] neg_lo:[0,1] neg_hi:[0,1]
	v_pk_add_f32 v[154:155], v[44:45], v[158:159] op_sel_hi:[1,0] neg_lo:[0,1] neg_hi:[0,1]
	v_pk_add_f32 v[168:169], v[24:25], v[172:173] op_sel_hi:[1,0] neg_lo:[0,1] neg_hi:[0,1]
	v_pk_add_f32 v[182:183], v[8:9], v[186:187] op_sel_hi:[1,0] neg_lo:[0,1] neg_hi:[0,1]
	v_pk_fma_f32 v[146:147], v[140:141], v[140:141], v[146:147]
	v_pk_fma_f32 v[160:161], v[154:155], v[154:155], v[160:161]
	v_pk_fma_f32 v[174:175], v[168:169], v[168:169], v[174:175]
	v_pk_fma_f32 v[188:189], v[182:183], v[182:183], v[188:189]
	v_pk_add_f32 v[142:143], v[62:63], v[144:145] op_sel_hi:[1,0] neg_lo:[0,1] neg_hi:[0,1]
	v_pk_add_f32 v[156:157], v[46:47], v[158:159] op_sel_hi:[1,0] neg_lo:[0,1] neg_hi:[0,1]
	v_pk_add_f32 v[170:171], v[26:27], v[172:173] op_sel_hi:[1,0] neg_lo:[0,1] neg_hi:[0,1]
	v_pk_add_f32 v[184:185], v[10:11], v[186:187] op_sel_hi:[1,0] neg_lo:[0,1] neg_hi:[0,1]
	v_pk_fma_f32 v[146:147], v[142:143], v[142:143], v[146:147]
	v_pk_fma_f32 v[160:161], v[156:157], v[156:157], v[160:161]
	v_pk_fma_f32 v[174:175], v[170:171], v[170:171], v[174:175]
	v_pk_fma_f32 v[188:189], v[184:185], v[184:185], v[188:189]
	v_pk_add_f32 v[136:137], v[56:57], v[144:145] op_sel_hi:[1,0] neg_lo:[0,1] neg_hi:[0,1]
; __device__ __forceinline__ float shx(float v, int mask) { return __builtin_bit_cast(float, __builtin_amdgcn_ds_bpermute((lane_now() ^ mask) << 2, __builtin_bit_cast(int, v))); }
;     __device__ __forceinline__ void fused(f32x4 (&acc)[2][2][4][2], const GUnit& u, int wr, int wc, int fr, int fq, LAS unsigned char* lds, int wid, int lane) const {
;     ...
;                     for (int n = 0; n < 2; ++n) { const f32x4 d = acc[ai][bj][m][n] - mw; q += (d[0] * d[0] + d[1] * d[1]) + (d[2] * d[2] + d[3] * d[3]); }
;                 q += shx(q, 16); q += shx(q, 32);
;                 if (fq == 0) P[(ai * 128 + wr * 64 + m * 16 + fr) * 4 + wc] = (f32x2){mw, q};
;             }
;         asm volatile("s_waitcnt lgkmcnt(0)" ::: "memory"); __builtin_amdgcn_s_barrier(); asm volatile("" ::: "memory");
;         const int prow = wid * 32 + (lane & 31);
;         if (lane < 32) {
;             const f32x2 a = P[prow * 4 + 0], b = P[prow * 4 + 1], c = P[prow * 4 + 2], d = P[prow * 4 + 3];
;             const float mt = (a.x + b.x + c.x + d.x) * 0.25f;
;             const float da = a.x - mt, db = b.x - mt, dc = c.x - mt, dd = d.x - mt;
;             const float m2 = (a.y + b.y) + (c.y + d.y) + 64.0f * ((da * da + db * db) + (dc * dc + dd * dd));
;             unsigned long long* slot = (unsigned long long*)xbuf + ((size_t)(u.pm * 256 + prow) * 4 + u.pn);
;             __hip_atomic_store(slot, ((unsigned long long)__float_as_uint(m2) << 32) | __float_as_uint(mt), __ATOMIC_RELAXED, __HIP_MEMORY_SCOPE_AGENT);
	v_pk_add_f32 v[150:151], v[40:41], v[158:159] op_sel_hi:[1,0] neg_lo:[0,1] neg_hi:[0,1]
	v_pk_add_f32 v[164:165], v[20:21], v[172:173] op_sel_hi:[1,0] neg_lo:[0,1] neg_hi:[0,1]
	v_pk_add_f32 v[178:179], v[4:5], v[186:187] op_sel_hi:[1,0] neg_lo:[0,1] neg_hi:[0,1]
	v_pk_fma_f32 v[146:147], v[136:137], v[136:137], v[146:147]
	v_pk_fma_f32 v[160:161], v[150:151], v[150:151], v[160:161]
	v_pk_fma_f32 v[174:175], v[164:165], v[164:165], v[174:175]
	v_pk_fma_f32 v[188:189], v[178:179], v[178:179], v[188:189]
	v_pk_add_f32 v[138:139], v[58:59], v[144:145] op_sel_hi:[1,0] neg_lo:[0,1] neg_hi:[0,1]
	v_pk_add_f32 v[152:153], v[42:43], v[158:159] op_sel_hi:[1,0] neg_lo:[0,1] neg_hi:[0,1]
	v_pk_add_f32 v[166:167], v[22:23], v[172:173] op_sel_hi:[1,0] neg_lo:[0,1] neg_hi:[0,1]
	v_pk_add_f32 v[180:181], v[6:7], v[186:187] op_sel_hi:[1,0] neg_lo:[0,1] neg_hi:[0,1]
	v_pk_fma_f32 v[146:147], v[138:139], v[138:139], v[146:147]
	v_pk_fma_f32 v[160:161], v[152:153], v[152:153], v[160:161]
	v_pk_fma_f32 v[174:175], v[166:167], v[166:167], v[174:175]
	v_pk_fma_f32 v[188:189], v[180:181], v[180:181], v[188:189]
	v_pk_add_f32 v[140:141], v[52:53], v[144:145] op_sel_hi:[1,0] neg_lo:[0,1] neg_hi:[0,1]
	v_pk_add_f32 v[154:155], v[36:37], v[158:159] op_sel_hi:[1,0] neg_lo:[0,1] neg_hi:[0,1]
	v_pk_add_f32 v[168:169], v[16:17], v[172:173] op_sel_hi:[1,0] neg_lo:[0,1] neg_hi:[0,1]
	v_pk_add_f32 v[182:183], v[0:1], v[186:187] op_sel_hi:[1,0] neg_lo:[0,1] neg_hi:[0,1]
	v_pk_fma_f32 v[146:147], v[140:141], v[140:141], v[146:147]
	v_pk_fma_f32 v[160:161], v[154:155], v[154:155], v[160:161]
	v_pk_fma_f32 v[174:175], v[168:169], v[168:169], v[174:175]
	v_pk_fma_f32 v[188:189], v[182:183], v[182:183], v[188:189]
	v_pk_add_f32 v[142:143], v[54:55], v[144:145] op_sel_hi:[1,0] neg_lo:[0,1] neg_hi:[0,1]
	v_pk_add_f32 v[156:157], v[38:39], v[158:159] op_sel_hi:[1,0] neg_lo:[0,1] neg_hi:[0,1]
	v_pk_add_f32 v[170:171], v[18:19], v[172:173] op_sel_hi:[1,0] neg_lo:[0,1] neg_hi:[0,1]
	v_pk_add_f32 v[184:185], v[2:3], v[186:187] op_sel_hi:[1,0] neg_lo:[0,1] neg_hi:[0,1]
	v_pk_fma_f32 v[146:147], v[142:143], v[142:143], v[146:147]
	v_pk_fma_f32 v[160:161], v[156:157], v[156:157], v[160:161]
	v_pk_fma_f32 v[174:175], v[170:171], v[170:171], v[174:175]
	v_pk_fma_f32 v[188:189], v[184:185], v[184:185], v[188:189]
	v_add_f32_e32 v145, v146, v147
	v_add_f32_e32 v159, v160, v161
	v_add_f32_e32 v173, v174, v175
	v_add_f32_e32 v187, v188, v189
	v_mov_b32_e32 v148, v145
	v_mov_b32_e32 v162, v159
	v_mov_b32_e32 v176, v173
	v_mov_b32_e32 v190, v187
	v_permlane16_swap_b32 v148, v145
	v_permlane16_swap_b32 v162, v159
	v_permlane16_swap_b32 v176, v173
	v_permlane16_swap_b32 v190, v187
	v_add_f32_e32 v145, v145, v148
	v_add_f32_e32 v159, v159, v162
	v_add_f32_e32 v173, v173, v176
	v_add_f32_e32 v187, v187, v190
	v_mov_b32_e32 v148, v145
	v_mov_b32_e32 v162, v159
	v_mov_b32_e32 v176, v173
	v_mov_b32_e32 v190, v187
	v_permlane32_swap_b32 v148, v145
	v_permlane32_swap_b32 v162, v159
	v_permlane32_swap_b32 v176, v173
	v_permlane32_swap_b32 v190, v187
	v_add_f32_e32 v145, v145, v148
	v_add_f32_e32 v159, v159, v162
	v_add_f32_e32 v173, v173, v176
	v_add_f32_e32 v187, v187, v190
	s_and_saveexec_b64 s[4:5], vcc
	ds_write_b64 v132, v[144:145] offset:4096
	ds_write_b64 v132, v[158:159] offset:4608
	ds_write_b64 v132, v[172:173] offset:5120
	ds_write_b64 v132, v[186:187] offset:5632
	s_or_b64 exec, exec, s[4:5]
	v_readlane_b32 s2, v251, 8
	s_waitcnt lgkmcnt(0)
	s_barrier
	v_cmp_gt_i32_e64 s[4:5], 32, v32
	v_and_or_b32 v134, v32, 31, s2
	v_add_u32_e32 v132, s14, v134
	v_ashrrev_i32_e32 v133, 31, v132
	s_and_saveexec_b64 s[2:3], s[4:5]
	s_cbranch_execz .LBB0_451
	s_waitcnt lgkmcnt(0)
	v_mov_b32_e32 v146, 0x24970
	ds_read_b32 v146, v146
	v_lshl_add_u32 v135, v134, 5, 0
	ds_read_b128 v[136:139], v135
	ds_read_b128 v[140:143], v135 offset:16
	v_readlane_b32 s6, v252, 14
	v_readlane_b32 s7, v252, 15
	s_ashr_i32 s35, s34, 31
	s_waitcnt lgkmcnt(1)
	v_add_f32_e32 v135, v136, v138
	s_waitcnt lgkmcnt(0)
	v_add_f32_e32 v135, v135, v140
	v_add_f32_e32 v135, v135, v142
	v_fmamk_f32 v136, v135, 0xbe800000, v136
	v_fmac_f32_e32 v138, 0xbe800000, v135
	v_fmamk_f32 v140, v135, 0xbe800000, v140
	v_fmac_f32_e32 v142, 0xbe800000, v135
	v_mul_f32_e32 v147, v136, v136
	v_mul_f32_e32 v149, v138, v138
	v_mul_f32_e32 v151, v140, v140
	v_mul_f32_e32 v153, v142, v142
	v_mov_b32_e32 v146, v137
	v_mov_b32_e32 v148, v139
	v_mov_b32_e32 v150, v141
	v_mov_b32_e32 v152, v143
	v_pk_add_f32 v[136:137], v[146:147], v[148:149]
	v_pk_add_f32 v[138:139], v[150:151], v[152:153]
	v_mul_f32_e32 v144, 0x3e800000, v135
	v_pk_add_f32 v[136:137], v[136:137], v[138:139]
	v_lshlrev_b64 v[138:139], 5, v[132:133]
	v_fmac_f32_e32 v136, 0x42800000, v137
	v_lshl_add_u64 v[138:139], s[6:7], 0, v[138:139]
	v_lshl_add_u64 v[138:139], s[34:35], 3, v[138:139]
	v_mov_b32_e32 v145, v136
	v_readfirstlane_b32 s98, v146
	s_nop 3
	s_cmp_eq_u32 s98, 0
	s_cbranch_scc1 .Lslot_sc1
	global_store_dwordx2 v[138:139], v[144:145], off
	s_branch .Lslot_done
